# branch-GEMM epilogue as one contiguous sequence with loads one block ahead
# speedup vs baseline: 1.0057x; 1.0057x over previous
.LBB0_90:
	v_mov_b32_e32 v136, s88
	ds_read_b32 v136, v136
	v_readlane_b32 s2, v254, 44
	v_mov_b32_e32 v151, v153
	s_mov_b64 s[58:59], -1
	s_mov_b64 s[56:57], 0
	s_waitcnt lgkmcnt(0)
	v_readfirstlane_b32 s48, v136
	v_mov_b32_e32 v136, s89
	ds_read_b32 v136, v136
	s_add_u32 s52, s48, 0x2100000
	s_waitcnt lgkmcnt(0)
	v_readfirstlane_b32 s49, v136
	v_mov_b32_e32 v136, s2
	ds_read_b32 v136, v136
	v_readlane_b32 s2, v254, 45
	s_addc_u32 s53, s49, 0
	s_add_u32 s46, s48, 0x158d0000
	s_addc_u32 s47, s49, 0
	s_waitcnt lgkmcnt(0)
	v_readfirstlane_b32 s42, v136
	v_mov_b32_e32 v136, s2
	ds_read_b32 v136, v136
	v_readlane_b32 s2, v254, 31
	s_add_u32 s40, s48, 0xc600000
	s_addc_u32 s41, s49, 0
	s_add_u32 s36, s48, 0xe700000
	s_waitcnt lgkmcnt(0)
	v_readfirstlane_b32 s43, v136
	v_mov_b32_e32 v136, s2
	ds_read_b32 v136, v136
	v_readlane_b32 s2, v254, 46
	s_addc_u32 s37, s49, 0
	s_add_u32 s34, s48, 0x6300000
	s_addc_u32 s35, s49, 0
	s_waitcnt lgkmcnt(0)
	v_readfirstlane_b32 s65, v136
	v_mov_b32_e32 v136, s2
	ds_read_b32 v136, v136
	v_readlane_b32 s2, v254, 39
	s_add_u32 s38, s48, 0x4200000
	s_addc_u32 s39, s49, 0
	s_add_u32 s50, s48, 0x15af4000
	s_waitcnt lgkmcnt(0)
	v_readfirstlane_b32 s66, v136
	v_mov_b32_e32 v136, s2
	ds_read_b32 v136, v136
	v_readlane_b32 s2, v254, 48
	s_addc_u32 s51, s49, 0
	s_lshl_b32 s62, s10, 8
	s_lshl_b32 s27, s67, 8
	s_waitcnt lgkmcnt(0)
	v_readfirstlane_b32 s44, v136
	v_mov_b32_e32 v136, s2
	v_readlane_b32 s2, v254, 40
	s_add_i32 s62, s62, s2
	s_ashr_i32 s2, s62, 13
	ds_read_b32 v136, v136
	s_mul_i32 s54, s2, 0x1800
	v_readlane_b32 s2, v254, 26
	s_ashr_i32 s55, s54, 31
	s_mul_i32 s2, s2, 0x12000
	s_add_u32 s2, s48, s2
	v_or_b32_e32 v138, s62, v157
	s_addc_u32 s3, s49, 0
	v_ashrrev_i32_e32 v139, 31, v138
	s_add_u32 s30, s2, 0x15ad0000
	s_waitcnt lgkmcnt(0)
	v_readfirstlane_b32 s45, v136
	v_lshlrev_b64 v[136:137], 13, v[138:139]
	v_add_u32_e32 v150, 0xffffc000, v138
	s_addc_u32 s31, s3, 0
	v_lshl_add_u64 v[148:149], s[52:53], 0, v[136:137]
	v_cmp_gt_i32_e64 s[10:11], s92, v138
	v_cmp_lt_i32_e64 s[8:9], s80, v138
	v_lshlrev_b64 v[146:147], 10, v[150:151]
	v_lshlrev_b64 v[142:143], 10, v[138:139]
	v_or_b32_e32 v136, s27, v161
	s_cmp_lt_i32 s79, 22
	s_cbranch_scc1 .Lfb_no
	s_cmp_gt_i32 s79, 24
	s_cbranch_scc1 .Lfb_no
	v_ashrrev_i32_e32 v137, 31, v136
	v_lshl_add_u64 v[140:141], v[142:143], 0, v[136:137]
	v_lshlrev_b64 v[140:141], 1, v[140:141]
	s_cmp_eq_u32 s79, 23
	s_cselect_b32 s2, s34, s40
	s_cselect_b32 s3, s35, s41
	s_cmp_eq_u32 s79, 22
	s_cselect_b32 s2, s38, s2
	s_cselect_b32 s3, s39, s3
	v_lshl_add_u64 v[244:245], s[2:3], 0, v[140:141]
	v_lshl_add_u64 v[246:247], s[36:37], 0, v[140:141]
	s_cbranch_scc1 .Lfb_k0
	v_mov_b32_e32 v236, v244
	v_mov_b32_e32 v237, v245
	global_load_dwordx2 v[194:195], v[236:237], off
	global_load_dwordx2 v[196:197], v[236:237], off offset:32
	v_mov_b32_e32 v236, v246
	v_mov_b32_e32 v237, v247
	global_load_dwordx2 v[198:199], v[236:237], off
	global_load_dwordx2 v[200:201], v[236:237], off offset:32
	v_add_co_u32_e32 v236, vcc, 0x100, v244
	v_addc_co_u32_e32 v237, vcc, 0, v245, vcc
	global_load_dwordx2 v[202:203], v[236:237], off
	global_load_dwordx2 v[204:205], v[236:237], off offset:32
	v_add_co_u32_e32 v236, vcc, 0x100, v246
	v_addc_co_u32_e32 v237, vcc, 0, v247, vcc
	global_load_dwordx2 v[206:207], v[236:237], off
	global_load_dwordx2 v[208:209], v[236:237], off offset:32
	s_waitcnt vmcnt(4)
	v_lshlrev_b32_e32 v230, 16, v194
	v_and_b32_e32 v231, 0xffff0000, v194
	v_lshlrev_b32_e32 v232, 16, v195
	v_and_b32_e32 v233, 0xffff0000, v195
	v_lshlrev_b32_e32 v234, 16, v198
	v_and_b32_e32 v235, 0xffff0000, v198
	v_lshlrev_b32_e32 v236, 16, v199
	v_and_b32_e32 v237, 0xffff0000, v199
	v_pk_fma_f32 v[230:231], v[124:125], v[230:231], v[234:235]
	v_pk_fma_f32 v[232:233], v[126:127], v[232:233], v[236:237]
	v_cvt_pk_bf16_f32 v230, v230, v231
	v_cvt_pk_bf16_f32 v231, v232, v233
	v_lshlrev_b32_e32 v194, 16, v196
	v_and_b32_e32 v195, 0xffff0000, v196
	v_lshlrev_b32_e32 v198, 16, v197
	v_and_b32_e32 v199, 0xffff0000, v197
	v_lshlrev_b32_e32 v234, 16, v200
	v_and_b32_e32 v235, 0xffff0000, v200
	v_lshlrev_b32_e32 v236, 16, v201
	v_and_b32_e32 v237, 0xffff0000, v201
	v_pk_fma_f32 v[194:195], v[120:121], v[194:195], v[234:235]
	v_pk_fma_f32 v[198:199], v[122:123], v[198:199], v[236:237]
	v_cvt_pk_bf16_f32 v232, v194, v195
	v_cvt_pk_bf16_f32 v233, v198, v199
	v_mov_b32_e32 v236, v246
	v_mov_b32_e32 v237, v247
	global_store_dwordx2 v[236:237], v[230:231], off
	global_store_dwordx2 v[236:237], v[232:233], off offset:32
	v_add_co_u32_e32 v236, vcc, 0x8000, v244
	v_addc_co_u32_e32 v237, vcc, 0, v245, vcc
	global_load_dwordx2 v[194:195], v[236:237], off
	global_load_dwordx2 v[196:197], v[236:237], off offset:32
	v_add_co_u32_e32 v236, vcc, 0x8000, v246
	v_addc_co_u32_e32 v237, vcc, 0, v247, vcc
	global_load_dwordx2 v[198:199], v[236:237], off
	global_load_dwordx2 v[200:201], v[236:237], off offset:32
	s_waitcnt vmcnt(6)
	v_lshlrev_b32_e32 v230, 16, v202
	v_and_b32_e32 v231, 0xffff0000, v202
	v_lshlrev_b32_e32 v232, 16, v203
	v_and_b32_e32 v233, 0xffff0000, v203
	v_lshlrev_b32_e32 v234, 16, v206
	v_and_b32_e32 v235, 0xffff0000, v206
	v_lshlrev_b32_e32 v236, 16, v207
	v_and_b32_e32 v237, 0xffff0000, v207
	v_pk_fma_f32 v[230:231], v[116:117], v[230:231], v[234:235]
	v_pk_fma_f32 v[232:233], v[118:119], v[232:233], v[236:237]
	v_cvt_pk_bf16_f32 v230, v230, v231
	v_cvt_pk_bf16_f32 v231, v232, v233
	v_lshlrev_b32_e32 v202, 16, v204
	v_and_b32_e32 v203, 0xffff0000, v204
	v_lshlrev_b32_e32 v206, 16, v205
	v_and_b32_e32 v207, 0xffff0000, v205
	v_lshlrev_b32_e32 v234, 16, v208
	v_and_b32_e32 v235, 0xffff0000, v208
	v_lshlrev_b32_e32 v236, 16, v209
	v_and_b32_e32 v237, 0xffff0000, v209
	v_pk_fma_f32 v[202:203], v[112:113], v[202:203], v[234:235]
	v_pk_fma_f32 v[206:207], v[114:115], v[206:207], v[236:237]
	v_cvt_pk_bf16_f32 v232, v202, v203
	v_cvt_pk_bf16_f32 v233, v206, v207
	v_add_co_u32_e32 v236, vcc, 0x100, v246
	v_addc_co_u32_e32 v237, vcc, 0, v247, vcc
	global_store_dwordx2 v[236:237], v[230:231], off
	global_store_dwordx2 v[236:237], v[232:233], off offset:32
	v_add_co_u32_e32 v236, vcc, 0x8100, v244
	v_addc_co_u32_e32 v237, vcc, 0, v245, vcc
	global_load_dwordx2 v[202:203], v[236:237], off
	global_load_dwordx2 v[204:205], v[236:237], off offset:32
	v_add_co_u32_e32 v236, vcc, 0x8100, v246
	v_addc_co_u32_e32 v237, vcc, 0, v247, vcc
	global_load_dwordx2 v[206:207], v[236:237], off
	global_load_dwordx2 v[208:209], v[236:237], off offset:32
	s_waitcnt vmcnt(6)
	v_lshlrev_b32_e32 v230, 16, v194
	v_and_b32_e32 v231, 0xffff0000, v194
	v_lshlrev_b32_e32 v232, 16, v195
	v_and_b32_e32 v233, 0xffff0000, v195
	v_lshlrev_b32_e32 v234, 16, v198
	v_and_b32_e32 v235, 0xffff0000, v198
	v_lshlrev_b32_e32 v236, 16, v199
	v_and_b32_e32 v237, 0xffff0000, v199
	v_pk_fma_f32 v[230:231], v[108:109], v[230:231], v[234:235]
	v_pk_fma_f32 v[232:233], v[110:111], v[232:233], v[236:237]
	v_cvt_pk_bf16_f32 v230, v230, v231
	v_cvt_pk_bf16_f32 v231, v232, v233
	v_lshlrev_b32_e32 v194, 16, v196
	v_and_b32_e32 v195, 0xffff0000, v196
	v_lshlrev_b32_e32 v198, 16, v197
	v_and_b32_e32 v199, 0xffff0000, v197
	v_lshlrev_b32_e32 v234, 16, v200
	v_and_b32_e32 v235, 0xffff0000, v200
	v_lshlrev_b32_e32 v236, 16, v201
	v_and_b32_e32 v237, 0xffff0000, v201
	v_pk_fma_f32 v[194:195], v[104:105], v[194:195], v[234:235]
	v_pk_fma_f32 v[198:199], v[106:107], v[198:199], v[236:237]
	v_cvt_pk_bf16_f32 v232, v194, v195
	v_cvt_pk_bf16_f32 v233, v198, v199
	v_add_co_u32_e32 v236, vcc, 0x8000, v246
	v_addc_co_u32_e32 v237, vcc, 0, v247, vcc
	global_store_dwordx2 v[236:237], v[230:231], off
	global_store_dwordx2 v[236:237], v[232:233], off offset:32
	v_add_co_u32_e32 v236, vcc, 0x10000, v244
	v_addc_co_u32_e32 v237, vcc, 0, v245, vcc
	global_load_dwordx2 v[194:195], v[236:237], off
	global_load_dwordx2 v[196:197], v[236:237], off offset:32
	v_add_co_u32_e32 v236, vcc, 0x10000, v246
	v_addc_co_u32_e32 v237, vcc, 0, v247, vcc
	global_load_dwordx2 v[198:199], v[236:237], off
	global_load_dwordx2 v[200:201], v[236:237], off offset:32
	s_waitcnt vmcnt(6)
	v_lshlrev_b32_e32 v230, 16, v202
	v_and_b32_e32 v231, 0xffff0000, v202
	v_lshlrev_b32_e32 v232, 16, v203
	v_and_b32_e32 v233, 0xffff0000, v203
	v_lshlrev_b32_e32 v234, 16, v206
	v_and_b32_e32 v235, 0xffff0000, v206
	v_lshlrev_b32_e32 v236, 16, v207
	v_and_b32_e32 v237, 0xffff0000, v207
	v_pk_fma_f32 v[230:231], v[100:101], v[230:231], v[234:235]
	v_pk_fma_f32 v[232:233], v[102:103], v[232:233], v[236:237]
	v_cvt_pk_bf16_f32 v230, v230, v231
	v_cvt_pk_bf16_f32 v231, v232, v233
	v_lshlrev_b32_e32 v202, 16, v204
	v_and_b32_e32 v203, 0xffff0000, v204
	v_lshlrev_b32_e32 v206, 16, v205
	v_and_b32_e32 v207, 0xffff0000, v205
	v_lshlrev_b32_e32 v234, 16, v208
	v_and_b32_e32 v235, 0xffff0000, v208
	v_lshlrev_b32_e32 v236, 16, v209
	v_and_b32_e32 v237, 0xffff0000, v209
	v_pk_fma_f32 v[202:203], v[96:97], v[202:203], v[234:235]
	v_pk_fma_f32 v[206:207], v[98:99], v[206:207], v[236:237]
	v_cvt_pk_bf16_f32 v232, v202, v203
	v_cvt_pk_bf16_f32 v233, v206, v207
	v_add_co_u32_e32 v236, vcc, 0x8100, v246
	v_addc_co_u32_e32 v237, vcc, 0, v247, vcc
	global_store_dwordx2 v[236:237], v[230:231], off
	global_store_dwordx2 v[236:237], v[232:233], off offset:32
	v_add_co_u32_e32 v236, vcc, 0x10100, v244
	v_addc_co_u32_e32 v237, vcc, 0, v245, vcc
	global_load_dwordx2 v[202:203], v[236:237], off
	global_load_dwordx2 v[204:205], v[236:237], off offset:32
	v_add_co_u32_e32 v236, vcc, 0x10100, v246
	v_addc_co_u32_e32 v237, vcc, 0, v247, vcc
	global_load_dwordx2 v[206:207], v[236:237], off
	global_load_dwordx2 v[208:209], v[236:237], off offset:32
	s_waitcnt vmcnt(6)
	v_lshlrev_b32_e32 v230, 16, v194
	v_and_b32_e32 v231, 0xffff0000, v194
	v_lshlrev_b32_e32 v232, 16, v195
	v_and_b32_e32 v233, 0xffff0000, v195
	v_lshlrev_b32_e32 v234, 16, v198
	v_and_b32_e32 v235, 0xffff0000, v198
	v_lshlrev_b32_e32 v236, 16, v199
	v_and_b32_e32 v237, 0xffff0000, v199
	v_pk_fma_f32 v[230:231], v[92:93], v[230:231], v[234:235]
	v_pk_fma_f32 v[232:233], v[94:95], v[232:233], v[236:237]
	v_cvt_pk_bf16_f32 v230, v230, v231
	v_cvt_pk_bf16_f32 v231, v232, v233
	v_lshlrev_b32_e32 v194, 16, v196
	v_and_b32_e32 v195, 0xffff0000, v196
	v_lshlrev_b32_e32 v198, 16, v197
	v_and_b32_e32 v199, 0xffff0000, v197
	v_lshlrev_b32_e32 v234, 16, v200
	v_and_b32_e32 v235, 0xffff0000, v200
	v_lshlrev_b32_e32 v236, 16, v201
	v_and_b32_e32 v237, 0xffff0000, v201
	v_pk_fma_f32 v[194:195], v[88:89], v[194:195], v[234:235]
	v_pk_fma_f32 v[198:199], v[90:91], v[198:199], v[236:237]
	v_cvt_pk_bf16_f32 v232, v194, v195
	v_cvt_pk_bf16_f32 v233, v198, v199
	v_add_co_u32_e32 v236, vcc, 0x10000, v246
	v_addc_co_u32_e32 v237, vcc, 0, v247, vcc
	global_store_dwordx2 v[236:237], v[230:231], off
	global_store_dwordx2 v[236:237], v[232:233], off offset:32
	v_add_co_u32_e32 v236, vcc, 0x18000, v244
	v_addc_co_u32_e32 v237, vcc, 0, v245, vcc
	global_load_dwordx2 v[194:195], v[236:237], off
	global_load_dwordx2 v[196:197], v[236:237], off offset:32
	v_add_co_u32_e32 v236, vcc, 0x18000, v246
	v_addc_co_u32_e32 v237, vcc, 0, v247, vcc
	global_load_dwordx2 v[198:199], v[236:237], off
	global_load_dwordx2 v[200:201], v[236:237], off offset:32
	s_waitcnt vmcnt(6)
	v_lshlrev_b32_e32 v230, 16, v202
	v_and_b32_e32 v231, 0xffff0000, v202
	v_lshlrev_b32_e32 v232, 16, v203
	v_and_b32_e32 v233, 0xffff0000, v203
	v_lshlrev_b32_e32 v234, 16, v206
	v_and_b32_e32 v235, 0xffff0000, v206
	v_lshlrev_b32_e32 v236, 16, v207
	v_and_b32_e32 v237, 0xffff0000, v207
	v_pk_fma_f32 v[230:231], v[84:85], v[230:231], v[234:235]
	v_pk_fma_f32 v[232:233], v[86:87], v[232:233], v[236:237]
	v_cvt_pk_bf16_f32 v230, v230, v231
	v_cvt_pk_bf16_f32 v231, v232, v233
	v_lshlrev_b32_e32 v202, 16, v204
	v_and_b32_e32 v203, 0xffff0000, v204
	v_lshlrev_b32_e32 v206, 16, v205
	v_and_b32_e32 v207, 0xffff0000, v205
	v_lshlrev_b32_e32 v234, 16, v208
	v_and_b32_e32 v235, 0xffff0000, v208
	v_lshlrev_b32_e32 v236, 16, v209
	v_and_b32_e32 v237, 0xffff0000, v209
	v_pk_fma_f32 v[202:203], v[80:81], v[202:203], v[234:235]
	v_pk_fma_f32 v[206:207], v[82:83], v[206:207], v[236:237]
	v_cvt_pk_bf16_f32 v232, v202, v203
	v_cvt_pk_bf16_f32 v233, v206, v207
	v_add_co_u32_e32 v236, vcc, 0x10100, v246
	v_addc_co_u32_e32 v237, vcc, 0, v247, vcc
	global_store_dwordx2 v[236:237], v[230:231], off
	global_store_dwordx2 v[236:237], v[232:233], off offset:32
	v_add_co_u32_e32 v236, vcc, 0x18100, v244
	v_addc_co_u32_e32 v237, vcc, 0, v245, vcc
	global_load_dwordx2 v[202:203], v[236:237], off
	global_load_dwordx2 v[204:205], v[236:237], off offset:32
	v_add_co_u32_e32 v236, vcc, 0x18100, v246
	v_addc_co_u32_e32 v237, vcc, 0, v247, vcc
	global_load_dwordx2 v[206:207], v[236:237], off
	global_load_dwordx2 v[208:209], v[236:237], off offset:32
	s_waitcnt vmcnt(6)
	v_lshlrev_b32_e32 v230, 16, v194
	v_and_b32_e32 v231, 0xffff0000, v194
	v_lshlrev_b32_e32 v232, 16, v195
	v_and_b32_e32 v233, 0xffff0000, v195
	v_lshlrev_b32_e32 v234, 16, v198
	v_and_b32_e32 v235, 0xffff0000, v198
	v_lshlrev_b32_e32 v236, 16, v199
	v_and_b32_e32 v237, 0xffff0000, v199
	v_pk_fma_f32 v[230:231], v[76:77], v[230:231], v[234:235]
	v_pk_fma_f32 v[232:233], v[78:79], v[232:233], v[236:237]
	v_cvt_pk_bf16_f32 v230, v230, v231
	v_cvt_pk_bf16_f32 v231, v232, v233
	v_lshlrev_b32_e32 v194, 16, v196
	v_and_b32_e32 v195, 0xffff0000, v196
	v_lshlrev_b32_e32 v198, 16, v197
	v_and_b32_e32 v199, 0xffff0000, v197
	v_lshlrev_b32_e32 v234, 16, v200
	v_and_b32_e32 v235, 0xffff0000, v200
	v_lshlrev_b32_e32 v236, 16, v201
	v_and_b32_e32 v237, 0xffff0000, v201
	v_pk_fma_f32 v[194:195], v[72:73], v[194:195], v[234:235]
	v_pk_fma_f32 v[198:199], v[74:75], v[198:199], v[236:237]
	v_cvt_pk_bf16_f32 v232, v194, v195
	v_cvt_pk_bf16_f32 v233, v198, v199
	v_add_co_u32_e32 v236, vcc, 0x18000, v246
	v_addc_co_u32_e32 v237, vcc, 0, v247, vcc
	global_store_dwordx2 v[236:237], v[230:231], off
	global_store_dwordx2 v[236:237], v[232:233], off offset:32
	v_add_co_u32_e32 v236, vcc, 0x40000, v244
	v_addc_co_u32_e32 v237, vcc, 0, v245, vcc
	global_load_dwordx2 v[194:195], v[236:237], off
	global_load_dwordx2 v[196:197], v[236:237], off offset:32
	v_add_co_u32_e32 v236, vcc, 0x40000, v246
	v_addc_co_u32_e32 v237, vcc, 0, v247, vcc
	global_load_dwordx2 v[198:199], v[236:237], off
	global_load_dwordx2 v[200:201], v[236:237], off offset:32
	s_waitcnt vmcnt(6)
	v_lshlrev_b32_e32 v230, 16, v202
	v_and_b32_e32 v231, 0xffff0000, v202
	v_lshlrev_b32_e32 v232, 16, v203
	v_and_b32_e32 v233, 0xffff0000, v203
	v_lshlrev_b32_e32 v234, 16, v206
	v_and_b32_e32 v235, 0xffff0000, v206
	v_lshlrev_b32_e32 v236, 16, v207
	v_and_b32_e32 v237, 0xffff0000, v207
	v_pk_fma_f32 v[230:231], v[68:69], v[230:231], v[234:235]
	v_pk_fma_f32 v[232:233], v[70:71], v[232:233], v[236:237]
	v_cvt_pk_bf16_f32 v230, v230, v231
	v_cvt_pk_bf16_f32 v231, v232, v233
	v_lshlrev_b32_e32 v202, 16, v204
	v_and_b32_e32 v203, 0xffff0000, v204
	v_lshlrev_b32_e32 v206, 16, v205
	v_and_b32_e32 v207, 0xffff0000, v205
	v_lshlrev_b32_e32 v234, 16, v208
	v_and_b32_e32 v235, 0xffff0000, v208
	v_lshlrev_b32_e32 v236, 16, v209
	v_and_b32_e32 v237, 0xffff0000, v209
	v_pk_fma_f32 v[202:203], v[64:65], v[202:203], v[234:235]
	v_pk_fma_f32 v[206:207], v[66:67], v[206:207], v[236:237]
	v_cvt_pk_bf16_f32 v232, v202, v203
	v_cvt_pk_bf16_f32 v233, v206, v207
	v_add_co_u32_e32 v236, vcc, 0x18100, v246
	v_addc_co_u32_e32 v237, vcc, 0, v247, vcc
	global_store_dwordx2 v[236:237], v[230:231], off
	global_store_dwordx2 v[236:237], v[232:233], off offset:32
	v_add_co_u32_e32 v236, vcc, 0x40100, v244
	v_addc_co_u32_e32 v237, vcc, 0, v245, vcc
	global_load_dwordx2 v[202:203], v[236:237], off
	global_load_dwordx2 v[204:205], v[236:237], off offset:32
	v_add_co_u32_e32 v236, vcc, 0x40100, v246
	v_addc_co_u32_e32 v237, vcc, 0, v247, vcc
	global_load_dwordx2 v[206:207], v[236:237], off
	global_load_dwordx2 v[208:209], v[236:237], off offset:32
	s_waitcnt vmcnt(6)
	v_lshlrev_b32_e32 v230, 16, v194
	v_and_b32_e32 v231, 0xffff0000, v194
	v_lshlrev_b32_e32 v232, 16, v195
	v_and_b32_e32 v233, 0xffff0000, v195
	v_lshlrev_b32_e32 v234, 16, v198
	v_and_b32_e32 v235, 0xffff0000, v198
	v_lshlrev_b32_e32 v236, 16, v199
	v_and_b32_e32 v237, 0xffff0000, v199
	v_pk_fma_f32 v[230:231], v[60:61], v[230:231], v[234:235]
	v_pk_fma_f32 v[232:233], v[62:63], v[232:233], v[236:237]
	v_cvt_pk_bf16_f32 v230, v230, v231
	v_cvt_pk_bf16_f32 v231, v232, v233
	v_lshlrev_b32_e32 v194, 16, v196
	v_and_b32_e32 v195, 0xffff0000, v196
	v_lshlrev_b32_e32 v198, 16, v197
	v_and_b32_e32 v199, 0xffff0000, v197
	v_lshlrev_b32_e32 v234, 16, v200
	v_and_b32_e32 v235, 0xffff0000, v200
	v_lshlrev_b32_e32 v236, 16, v201
	v_and_b32_e32 v237, 0xffff0000, v201
	v_pk_fma_f32 v[194:195], v[56:57], v[194:195], v[234:235]
	v_pk_fma_f32 v[198:199], v[58:59], v[198:199], v[236:237]
	v_cvt_pk_bf16_f32 v232, v194, v195
	v_cvt_pk_bf16_f32 v233, v198, v199
	v_add_co_u32_e32 v236, vcc, 0x40000, v246
	v_addc_co_u32_e32 v237, vcc, 0, v247, vcc
	global_store_dwordx2 v[236:237], v[230:231], off
	global_store_dwordx2 v[236:237], v[232:233], off offset:32
	v_add_co_u32_e32 v236, vcc, 0x48000, v244
	v_addc_co_u32_e32 v237, vcc, 0, v245, vcc
	global_load_dwordx2 v[194:195], v[236:237], off
	global_load_dwordx2 v[196:197], v[236:237], off offset:32
	v_add_co_u32_e32 v236, vcc, 0x48000, v246
	v_addc_co_u32_e32 v237, vcc, 0, v247, vcc
	global_load_dwordx2 v[198:199], v[236:237], off
	global_load_dwordx2 v[200:201], v[236:237], off offset:32
	s_waitcnt vmcnt(6)
	v_lshlrev_b32_e32 v230, 16, v202
	v_and_b32_e32 v231, 0xffff0000, v202
	v_lshlrev_b32_e32 v232, 16, v203
	v_and_b32_e32 v233, 0xffff0000, v203
	v_lshlrev_b32_e32 v234, 16, v206
	v_and_b32_e32 v235, 0xffff0000, v206
	v_lshlrev_b32_e32 v236, 16, v207
	v_and_b32_e32 v237, 0xffff0000, v207
	v_pk_fma_f32 v[230:231], v[52:53], v[230:231], v[234:235]
	v_pk_fma_f32 v[232:233], v[54:55], v[232:233], v[236:237]
	v_cvt_pk_bf16_f32 v230, v230, v231
	v_cvt_pk_bf16_f32 v231, v232, v233
	v_lshlrev_b32_e32 v202, 16, v204
	v_and_b32_e32 v203, 0xffff0000, v204
	v_lshlrev_b32_e32 v206, 16, v205
	v_and_b32_e32 v207, 0xffff0000, v205
	v_lshlrev_b32_e32 v234, 16, v208
	v_and_b32_e32 v235, 0xffff0000, v208
	v_lshlrev_b32_e32 v236, 16, v209
	v_and_b32_e32 v237, 0xffff0000, v209
	v_pk_fma_f32 v[202:203], v[48:49], v[202:203], v[234:235]
	v_pk_fma_f32 v[206:207], v[50:51], v[206:207], v[236:237]
	v_cvt_pk_bf16_f32 v232, v202, v203
	v_cvt_pk_bf16_f32 v233, v206, v207
	v_add_co_u32_e32 v236, vcc, 0x40100, v246
	v_addc_co_u32_e32 v237, vcc, 0, v247, vcc
	global_store_dwordx2 v[236:237], v[230:231], off
	global_store_dwordx2 v[236:237], v[232:233], off offset:32
	v_add_co_u32_e32 v236, vcc, 0x48100, v244
	v_addc_co_u32_e32 v237, vcc, 0, v245, vcc
	global_load_dwordx2 v[202:203], v[236:237], off
	global_load_dwordx2 v[204:205], v[236:237], off offset:32
	v_add_co_u32_e32 v236, vcc, 0x48100, v246
	v_addc_co_u32_e32 v237, vcc, 0, v247, vcc
	global_load_dwordx2 v[206:207], v[236:237], off
	global_load_dwordx2 v[208:209], v[236:237], off offset:32
	s_waitcnt vmcnt(6)
	v_lshlrev_b32_e32 v230, 16, v194
	v_and_b32_e32 v231, 0xffff0000, v194
	v_lshlrev_b32_e32 v232, 16, v195
	v_and_b32_e32 v233, 0xffff0000, v195
	v_lshlrev_b32_e32 v234, 16, v198
	v_and_b32_e32 v235, 0xffff0000, v198
	v_lshlrev_b32_e32 v236, 16, v199
	v_and_b32_e32 v237, 0xffff0000, v199
	v_pk_fma_f32 v[230:231], v[44:45], v[230:231], v[234:235]
	v_pk_fma_f32 v[232:233], v[46:47], v[232:233], v[236:237]
	v_cvt_pk_bf16_f32 v230, v230, v231
	v_cvt_pk_bf16_f32 v231, v232, v233
	v_lshlrev_b32_e32 v194, 16, v196
	v_and_b32_e32 v195, 0xffff0000, v196
	v_lshlrev_b32_e32 v198, 16, v197
	v_and_b32_e32 v199, 0xffff0000, v197
	v_lshlrev_b32_e32 v234, 16, v200
	v_and_b32_e32 v235, 0xffff0000, v200
	v_lshlrev_b32_e32 v236, 16, v201
	v_and_b32_e32 v237, 0xffff0000, v201
	v_pk_fma_f32 v[194:195], v[40:41], v[194:195], v[234:235]
	v_pk_fma_f32 v[198:199], v[42:43], v[198:199], v[236:237]
	v_cvt_pk_bf16_f32 v232, v194, v195
	v_cvt_pk_bf16_f32 v233, v198, v199
	v_add_co_u32_e32 v236, vcc, 0x48000, v246
	v_addc_co_u32_e32 v237, vcc, 0, v247, vcc
	global_store_dwordx2 v[236:237], v[230:231], off
	global_store_dwordx2 v[236:237], v[232:233], off offset:32
	v_add_co_u32_e32 v236, vcc, 0x50000, v244
	v_addc_co_u32_e32 v237, vcc, 0, v245, vcc
	global_load_dwordx2 v[194:195], v[236:237], off
	global_load_dwordx2 v[196:197], v[236:237], off offset:32
	v_add_co_u32_e32 v236, vcc, 0x50000, v246
	v_addc_co_u32_e32 v237, vcc, 0, v247, vcc
	global_load_dwordx2 v[198:199], v[236:237], off
	global_load_dwordx2 v[200:201], v[236:237], off offset:32
	s_waitcnt vmcnt(6)
	v_lshlrev_b32_e32 v230, 16, v202
	v_and_b32_e32 v231, 0xffff0000, v202
	v_lshlrev_b32_e32 v232, 16, v203
	v_and_b32_e32 v233, 0xffff0000, v203
	v_lshlrev_b32_e32 v234, 16, v206
	v_and_b32_e32 v235, 0xffff0000, v206
	v_lshlrev_b32_e32 v236, 16, v207
	v_and_b32_e32 v237, 0xffff0000, v207
	v_pk_fma_f32 v[230:231], v[36:37], v[230:231], v[234:235]
	v_pk_fma_f32 v[232:233], v[38:39], v[232:233], v[236:237]
	v_cvt_pk_bf16_f32 v230, v230, v231
	v_cvt_pk_bf16_f32 v231, v232, v233
	v_lshlrev_b32_e32 v202, 16, v204
	v_and_b32_e32 v203, 0xffff0000, v204
	v_lshlrev_b32_e32 v206, 16, v205
	v_and_b32_e32 v207, 0xffff0000, v205
	v_lshlrev_b32_e32 v234, 16, v208
	v_and_b32_e32 v235, 0xffff0000, v208
	v_lshlrev_b32_e32 v236, 16, v209
	v_and_b32_e32 v237, 0xffff0000, v209
	v_pk_fma_f32 v[202:203], v[32:33], v[202:203], v[234:235]
	v_pk_fma_f32 v[206:207], v[34:35], v[206:207], v[236:237]
	v_cvt_pk_bf16_f32 v232, v202, v203
	v_cvt_pk_bf16_f32 v233, v206, v207
	v_add_co_u32_e32 v236, vcc, 0x48100, v246
	v_addc_co_u32_e32 v237, vcc, 0, v247, vcc
	global_store_dwordx2 v[236:237], v[230:231], off
	global_store_dwordx2 v[236:237], v[232:233], off offset:32
	v_add_co_u32_e32 v236, vcc, 0x50100, v244
	v_addc_co_u32_e32 v237, vcc, 0, v245, vcc
	global_load_dwordx2 v[202:203], v[236:237], off
	global_load_dwordx2 v[204:205], v[236:237], off offset:32
	v_add_co_u32_e32 v236, vcc, 0x50100, v246
	v_addc_co_u32_e32 v237, vcc, 0, v247, vcc
	global_load_dwordx2 v[206:207], v[236:237], off
	global_load_dwordx2 v[208:209], v[236:237], off offset:32
	s_waitcnt vmcnt(6)
	v_lshlrev_b32_e32 v230, 16, v194
	v_and_b32_e32 v231, 0xffff0000, v194
	v_lshlrev_b32_e32 v232, 16, v195
	v_and_b32_e32 v233, 0xffff0000, v195
	v_lshlrev_b32_e32 v234, 16, v198
	v_and_b32_e32 v235, 0xffff0000, v198
	v_lshlrev_b32_e32 v236, 16, v199
	v_and_b32_e32 v237, 0xffff0000, v199
	v_pk_fma_f32 v[230:231], v[28:29], v[230:231], v[234:235]
	v_pk_fma_f32 v[232:233], v[30:31], v[232:233], v[236:237]
	v_cvt_pk_bf16_f32 v230, v230, v231
	v_cvt_pk_bf16_f32 v231, v232, v233
	v_lshlrev_b32_e32 v194, 16, v196
	v_and_b32_e32 v195, 0xffff0000, v196
	v_lshlrev_b32_e32 v198, 16, v197
	v_and_b32_e32 v199, 0xffff0000, v197
	v_lshlrev_b32_e32 v234, 16, v200
	v_and_b32_e32 v235, 0xffff0000, v200
	v_lshlrev_b32_e32 v236, 16, v201
	v_and_b32_e32 v237, 0xffff0000, v201
	v_pk_fma_f32 v[194:195], v[24:25], v[194:195], v[234:235]
	v_pk_fma_f32 v[198:199], v[26:27], v[198:199], v[236:237]
	v_cvt_pk_bf16_f32 v232, v194, v195
	v_cvt_pk_bf16_f32 v233, v198, v199
	v_add_co_u32_e32 v236, vcc, 0x50000, v246
	v_addc_co_u32_e32 v237, vcc, 0, v247, vcc
	global_store_dwordx2 v[236:237], v[230:231], off
	global_store_dwordx2 v[236:237], v[232:233], off offset:32
	v_add_co_u32_e32 v236, vcc, 0x58000, v244
	v_addc_co_u32_e32 v237, vcc, 0, v245, vcc
	global_load_dwordx2 v[194:195], v[236:237], off
	global_load_dwordx2 v[196:197], v[236:237], off offset:32
	v_add_co_u32_e32 v236, vcc, 0x58000, v246
	v_addc_co_u32_e32 v237, vcc, 0, v247, vcc
	global_load_dwordx2 v[198:199], v[236:237], off
	global_load_dwordx2 v[200:201], v[236:237], off offset:32
	s_waitcnt vmcnt(6)
	v_lshlrev_b32_e32 v230, 16, v202
	v_and_b32_e32 v231, 0xffff0000, v202
	v_lshlrev_b32_e32 v232, 16, v203
	v_and_b32_e32 v233, 0xffff0000, v203
	v_lshlrev_b32_e32 v234, 16, v206
	v_and_b32_e32 v235, 0xffff0000, v206
	v_lshlrev_b32_e32 v236, 16, v207
	v_and_b32_e32 v237, 0xffff0000, v207
	v_pk_fma_f32 v[230:231], v[20:21], v[230:231], v[234:235]
	v_pk_fma_f32 v[232:233], v[22:23], v[232:233], v[236:237]
	v_cvt_pk_bf16_f32 v230, v230, v231
	v_cvt_pk_bf16_f32 v231, v232, v233
	v_lshlrev_b32_e32 v202, 16, v204
	v_and_b32_e32 v203, 0xffff0000, v204
	v_lshlrev_b32_e32 v206, 16, v205
	v_and_b32_e32 v207, 0xffff0000, v205
	v_lshlrev_b32_e32 v234, 16, v208
	v_and_b32_e32 v235, 0xffff0000, v208
	v_lshlrev_b32_e32 v236, 16, v209
	v_and_b32_e32 v237, 0xffff0000, v209
	v_pk_fma_f32 v[202:203], v[16:17], v[202:203], v[234:235]
	v_pk_fma_f32 v[206:207], v[18:19], v[206:207], v[236:237]
	v_cvt_pk_bf16_f32 v232, v202, v203
	v_cvt_pk_bf16_f32 v233, v206, v207
	v_add_co_u32_e32 v236, vcc, 0x50100, v246
	v_addc_co_u32_e32 v237, vcc, 0, v247, vcc
	global_store_dwordx2 v[236:237], v[230:231], off
	global_store_dwordx2 v[236:237], v[232:233], off offset:32
	v_add_co_u32_e32 v236, vcc, 0x58100, v244
	v_addc_co_u32_e32 v237, vcc, 0, v245, vcc
	global_load_dwordx2 v[202:203], v[236:237], off
	global_load_dwordx2 v[204:205], v[236:237], off offset:32
	v_add_co_u32_e32 v236, vcc, 0x58100, v246
	v_addc_co_u32_e32 v237, vcc, 0, v247, vcc
	global_load_dwordx2 v[206:207], v[236:237], off
	global_load_dwordx2 v[208:209], v[236:237], off offset:32
	s_waitcnt vmcnt(6)
	v_lshlrev_b32_e32 v230, 16, v194
	v_and_b32_e32 v231, 0xffff0000, v194
	v_lshlrev_b32_e32 v232, 16, v195
	v_and_b32_e32 v233, 0xffff0000, v195
	v_lshlrev_b32_e32 v234, 16, v198
	v_and_b32_e32 v235, 0xffff0000, v198
	v_lshlrev_b32_e32 v236, 16, v199
	v_and_b32_e32 v237, 0xffff0000, v199
	v_pk_fma_f32 v[230:231], v[12:13], v[230:231], v[234:235]
	v_pk_fma_f32 v[232:233], v[14:15], v[232:233], v[236:237]
	v_cvt_pk_bf16_f32 v230, v230, v231
	v_cvt_pk_bf16_f32 v231, v232, v233
	v_lshlrev_b32_e32 v194, 16, v196
	v_and_b32_e32 v195, 0xffff0000, v196
	v_lshlrev_b32_e32 v198, 16, v197
	v_and_b32_e32 v199, 0xffff0000, v197
	v_lshlrev_b32_e32 v234, 16, v200
	v_and_b32_e32 v235, 0xffff0000, v200
	v_lshlrev_b32_e32 v236, 16, v201
	v_and_b32_e32 v237, 0xffff0000, v201
	v_pk_fma_f32 v[194:195], v[8:9], v[194:195], v[234:235]
	v_pk_fma_f32 v[198:199], v[10:11], v[198:199], v[236:237]
	v_cvt_pk_bf16_f32 v232, v194, v195
	v_cvt_pk_bf16_f32 v233, v198, v199
	v_add_co_u32_e32 v236, vcc, 0x58000, v246
	v_addc_co_u32_e32 v237, vcc, 0, v247, vcc
	global_store_dwordx2 v[236:237], v[230:231], off
	global_store_dwordx2 v[236:237], v[232:233], off offset:32
	s_waitcnt vmcnt(2)
	v_lshlrev_b32_e32 v230, 16, v202
	v_and_b32_e32 v231, 0xffff0000, v202
	v_lshlrev_b32_e32 v232, 16, v203
	v_and_b32_e32 v233, 0xffff0000, v203
	v_lshlrev_b32_e32 v234, 16, v206
	v_and_b32_e32 v235, 0xffff0000, v206
	v_lshlrev_b32_e32 v236, 16, v207
	v_and_b32_e32 v237, 0xffff0000, v207
	v_pk_fma_f32 v[230:231], v[4:5], v[230:231], v[234:235]
	v_pk_fma_f32 v[232:233], v[6:7], v[232:233], v[236:237]
	v_cvt_pk_bf16_f32 v230, v230, v231
	v_cvt_pk_bf16_f32 v231, v232, v233
	v_lshlrev_b32_e32 v202, 16, v204
	v_and_b32_e32 v203, 0xffff0000, v204
	v_lshlrev_b32_e32 v206, 16, v205
	v_and_b32_e32 v207, 0xffff0000, v205
	v_lshlrev_b32_e32 v234, 16, v208
	v_and_b32_e32 v235, 0xffff0000, v208
	v_lshlrev_b32_e32 v236, 16, v209
	v_and_b32_e32 v237, 0xffff0000, v209
	v_pk_fma_f32 v[202:203], v[0:1], v[202:203], v[234:235]
	v_pk_fma_f32 v[206:207], v[2:3], v[206:207], v[236:237]
	v_cvt_pk_bf16_f32 v232, v202, v203
	v_cvt_pk_bf16_f32 v233, v206, v207
	v_add_co_u32_e32 v236, vcc, 0x58100, v246
	v_addc_co_u32_e32 v237, vcc, 0, v247, vcc
	global_store_dwordx2 v[236:237], v[230:231], off
	global_store_dwordx2 v[236:237], v[232:233], off offset:32
	s_branch .LBB0_1065
.Lfb_k0:
	v_mov_b32_e32 v236, v244
	v_mov_b32_e32 v237, v245
	global_load_dwordx2 v[194:195], v[236:237], off
	global_load_dwordx2 v[196:197], v[236:237], off offset:32
	v_add_co_u32_e32 v236, vcc, 0x100, v244
	v_addc_co_u32_e32 v237, vcc, 0, v245, vcc
	global_load_dwordx2 v[202:203], v[236:237], off
	global_load_dwordx2 v[204:205], v[236:237], off offset:32
	s_waitcnt vmcnt(2)
	v_lshlrev_b32_e32 v230, 16, v194
	v_and_b32_e32 v231, 0xffff0000, v194
	v_lshlrev_b32_e32 v232, 16, v195
	v_and_b32_e32 v233, 0xffff0000, v195
	v_pk_mul_f32 v[230:231], v[124:125], v[230:231]
	v_pk_mul_f32 v[232:233], v[126:127], v[232:233]
	v_cvt_pk_bf16_f32 v230, v230, v231
	v_cvt_pk_bf16_f32 v231, v232, v233
	v_lshlrev_b32_e32 v234, 16, v196
	v_and_b32_e32 v235, 0xffff0000, v196
	v_lshlrev_b32_e32 v236, 16, v197
	v_and_b32_e32 v237, 0xffff0000, v197
	v_pk_mul_f32 v[234:235], v[120:121], v[234:235]
	v_pk_mul_f32 v[236:237], v[122:123], v[236:237]
	v_cvt_pk_bf16_f32 v232, v234, v235
	v_cvt_pk_bf16_f32 v233, v236, v237
	v_mov_b32_e32 v236, v246
	v_mov_b32_e32 v237, v247
	global_store_dwordx2 v[236:237], v[230:231], off
	global_store_dwordx2 v[236:237], v[232:233], off offset:32
	v_add_co_u32_e32 v236, vcc, 0x8000, v244
	v_addc_co_u32_e32 v237, vcc, 0, v245, vcc
	global_load_dwordx2 v[194:195], v[236:237], off
	global_load_dwordx2 v[196:197], v[236:237], off offset:32
	s_waitcnt vmcnt(4)
	v_lshlrev_b32_e32 v230, 16, v202
	v_and_b32_e32 v231, 0xffff0000, v202
	v_lshlrev_b32_e32 v232, 16, v203
	v_and_b32_e32 v233, 0xffff0000, v203
	v_pk_mul_f32 v[230:231], v[116:117], v[230:231]
	v_pk_mul_f32 v[232:233], v[118:119], v[232:233]
	v_cvt_pk_bf16_f32 v230, v230, v231
	v_cvt_pk_bf16_f32 v231, v232, v233
	v_lshlrev_b32_e32 v234, 16, v204
	v_and_b32_e32 v235, 0xffff0000, v204
	v_lshlrev_b32_e32 v236, 16, v205
	v_and_b32_e32 v237, 0xffff0000, v205
	v_pk_mul_f32 v[234:235], v[112:113], v[234:235]
	v_pk_mul_f32 v[236:237], v[114:115], v[236:237]
	v_cvt_pk_bf16_f32 v232, v234, v235
	v_cvt_pk_bf16_f32 v233, v236, v237
	v_add_co_u32_e32 v236, vcc, 0x100, v246
	v_addc_co_u32_e32 v237, vcc, 0, v247, vcc
	global_store_dwordx2 v[236:237], v[230:231], off
	global_store_dwordx2 v[236:237], v[232:233], off offset:32
	v_add_co_u32_e32 v236, vcc, 0x8100, v244
	v_addc_co_u32_e32 v237, vcc, 0, v245, vcc
	global_load_dwordx2 v[202:203], v[236:237], off
	global_load_dwordx2 v[204:205], v[236:237], off offset:32
	s_waitcnt vmcnt(4)
	v_lshlrev_b32_e32 v230, 16, v194
	v_and_b32_e32 v231, 0xffff0000, v194
	v_lshlrev_b32_e32 v232, 16, v195
	v_and_b32_e32 v233, 0xffff0000, v195
	v_pk_mul_f32 v[230:231], v[108:109], v[230:231]
	v_pk_mul_f32 v[232:233], v[110:111], v[232:233]
	v_cvt_pk_bf16_f32 v230, v230, v231
	v_cvt_pk_bf16_f32 v231, v232, v233
	v_lshlrev_b32_e32 v234, 16, v196
	v_and_b32_e32 v235, 0xffff0000, v196
	v_lshlrev_b32_e32 v236, 16, v197
	v_and_b32_e32 v237, 0xffff0000, v197
	v_pk_mul_f32 v[234:235], v[104:105], v[234:235]
	v_pk_mul_f32 v[236:237], v[106:107], v[236:237]
	v_cvt_pk_bf16_f32 v232, v234, v235
	v_cvt_pk_bf16_f32 v233, v236, v237
	v_add_co_u32_e32 v236, vcc, 0x8000, v246
	v_addc_co_u32_e32 v237, vcc, 0, v247, vcc
	global_store_dwordx2 v[236:237], v[230:231], off
	global_store_dwordx2 v[236:237], v[232:233], off offset:32
	v_add_co_u32_e32 v236, vcc, 0x10000, v244
	v_addc_co_u32_e32 v237, vcc, 0, v245, vcc
	global_load_dwordx2 v[194:195], v[236:237], off
	global_load_dwordx2 v[196:197], v[236:237], off offset:32
	s_waitcnt vmcnt(4)
	v_lshlrev_b32_e32 v230, 16, v202
	v_and_b32_e32 v231, 0xffff0000, v202
	v_lshlrev_b32_e32 v232, 16, v203
	v_and_b32_e32 v233, 0xffff0000, v203
	v_pk_mul_f32 v[230:231], v[100:101], v[230:231]
	v_pk_mul_f32 v[232:233], v[102:103], v[232:233]
	v_cvt_pk_bf16_f32 v230, v230, v231
	v_cvt_pk_bf16_f32 v231, v232, v233
	v_lshlrev_b32_e32 v234, 16, v204
	v_and_b32_e32 v235, 0xffff0000, v204
	v_lshlrev_b32_e32 v236, 16, v205
	v_and_b32_e32 v237, 0xffff0000, v205
	v_pk_mul_f32 v[234:235], v[96:97], v[234:235]
	v_pk_mul_f32 v[236:237], v[98:99], v[236:237]
	v_cvt_pk_bf16_f32 v232, v234, v235
	v_cvt_pk_bf16_f32 v233, v236, v237
	v_add_co_u32_e32 v236, vcc, 0x8100, v246
	v_addc_co_u32_e32 v237, vcc, 0, v247, vcc
	global_store_dwordx2 v[236:237], v[230:231], off
	global_store_dwordx2 v[236:237], v[232:233], off offset:32
	v_add_co_u32_e32 v236, vcc, 0x10100, v244
	v_addc_co_u32_e32 v237, vcc, 0, v245, vcc
	global_load_dwordx2 v[202:203], v[236:237], off
	global_load_dwordx2 v[204:205], v[236:237], off offset:32
	s_waitcnt vmcnt(4)
	v_lshlrev_b32_e32 v230, 16, v194
	v_and_b32_e32 v231, 0xffff0000, v194
	v_lshlrev_b32_e32 v232, 16, v195
	v_and_b32_e32 v233, 0xffff0000, v195
	v_pk_mul_f32 v[230:231], v[92:93], v[230:231]
	v_pk_mul_f32 v[232:233], v[94:95], v[232:233]
	v_cvt_pk_bf16_f32 v230, v230, v231
	v_cvt_pk_bf16_f32 v231, v232, v233
	v_lshlrev_b32_e32 v234, 16, v196
	v_and_b32_e32 v235, 0xffff0000, v196
	v_lshlrev_b32_e32 v236, 16, v197
	v_and_b32_e32 v237, 0xffff0000, v197
	v_pk_mul_f32 v[234:235], v[88:89], v[234:235]
	v_pk_mul_f32 v[236:237], v[90:91], v[236:237]
	v_cvt_pk_bf16_f32 v232, v234, v235
	v_cvt_pk_bf16_f32 v233, v236, v237
	v_add_co_u32_e32 v236, vcc, 0x10000, v246
	v_addc_co_u32_e32 v237, vcc, 0, v247, vcc
	global_store_dwordx2 v[236:237], v[230:231], off
	global_store_dwordx2 v[236:237], v[232:233], off offset:32
	v_add_co_u32_e32 v236, vcc, 0x18000, v244
	v_addc_co_u32_e32 v237, vcc, 0, v245, vcc
	global_load_dwordx2 v[194:195], v[236:237], off
	global_load_dwordx2 v[196:197], v[236:237], off offset:32
	s_waitcnt vmcnt(4)
	v_lshlrev_b32_e32 v230, 16, v202
	v_and_b32_e32 v231, 0xffff0000, v202
	v_lshlrev_b32_e32 v232, 16, v203
	v_and_b32_e32 v233, 0xffff0000, v203
	v_pk_mul_f32 v[230:231], v[84:85], v[230:231]
	v_pk_mul_f32 v[232:233], v[86:87], v[232:233]
	v_cvt_pk_bf16_f32 v230, v230, v231
	v_cvt_pk_bf16_f32 v231, v232, v233
	v_lshlrev_b32_e32 v234, 16, v204
	v_and_b32_e32 v235, 0xffff0000, v204
	v_lshlrev_b32_e32 v236, 16, v205
	v_and_b32_e32 v237, 0xffff0000, v205
	v_pk_mul_f32 v[234:235], v[80:81], v[234:235]
	v_pk_mul_f32 v[236:237], v[82:83], v[236:237]
	v_cvt_pk_bf16_f32 v232, v234, v235
	v_cvt_pk_bf16_f32 v233, v236, v237
	v_add_co_u32_e32 v236, vcc, 0x10100, v246
	v_addc_co_u32_e32 v237, vcc, 0, v247, vcc
	global_store_dwordx2 v[236:237], v[230:231], off
	global_store_dwordx2 v[236:237], v[232:233], off offset:32
	v_add_co_u32_e32 v236, vcc, 0x18100, v244
	v_addc_co_u32_e32 v237, vcc, 0, v245, vcc
	global_load_dwordx2 v[202:203], v[236:237], off
	global_load_dwordx2 v[204:205], v[236:237], off offset:32
	s_waitcnt vmcnt(4)
	v_lshlrev_b32_e32 v230, 16, v194
	v_and_b32_e32 v231, 0xffff0000, v194
	v_lshlrev_b32_e32 v232, 16, v195
	v_and_b32_e32 v233, 0xffff0000, v195
	v_pk_mul_f32 v[230:231], v[76:77], v[230:231]
	v_pk_mul_f32 v[232:233], v[78:79], v[232:233]
	v_cvt_pk_bf16_f32 v230, v230, v231
	v_cvt_pk_bf16_f32 v231, v232, v233
	v_lshlrev_b32_e32 v234, 16, v196
	v_and_b32_e32 v235, 0xffff0000, v196
	v_lshlrev_b32_e32 v236, 16, v197
	v_and_b32_e32 v237, 0xffff0000, v197
	v_pk_mul_f32 v[234:235], v[72:73], v[234:235]
	v_pk_mul_f32 v[236:237], v[74:75], v[236:237]
	v_cvt_pk_bf16_f32 v232, v234, v235
	v_cvt_pk_bf16_f32 v233, v236, v237
	v_add_co_u32_e32 v236, vcc, 0x18000, v246
	v_addc_co_u32_e32 v237, vcc, 0, v247, vcc
	global_store_dwordx2 v[236:237], v[230:231], off
	global_store_dwordx2 v[236:237], v[232:233], off offset:32
	v_add_co_u32_e32 v236, vcc, 0x40000, v244
	v_addc_co_u32_e32 v237, vcc, 0, v245, vcc
	global_load_dwordx2 v[194:195], v[236:237], off
	global_load_dwordx2 v[196:197], v[236:237], off offset:32
	s_waitcnt vmcnt(4)
	v_lshlrev_b32_e32 v230, 16, v202
	v_and_b32_e32 v231, 0xffff0000, v202
	v_lshlrev_b32_e32 v232, 16, v203
	v_and_b32_e32 v233, 0xffff0000, v203
	v_pk_mul_f32 v[230:231], v[68:69], v[230:231]
	v_pk_mul_f32 v[232:233], v[70:71], v[232:233]
	v_cvt_pk_bf16_f32 v230, v230, v231
	v_cvt_pk_bf16_f32 v231, v232, v233
	v_lshlrev_b32_e32 v234, 16, v204
	v_and_b32_e32 v235, 0xffff0000, v204
	v_lshlrev_b32_e32 v236, 16, v205
	v_and_b32_e32 v237, 0xffff0000, v205
	v_pk_mul_f32 v[234:235], v[64:65], v[234:235]
	v_pk_mul_f32 v[236:237], v[66:67], v[236:237]
	v_cvt_pk_bf16_f32 v232, v234, v235
	v_cvt_pk_bf16_f32 v233, v236, v237
	v_add_co_u32_e32 v236, vcc, 0x18100, v246
	v_addc_co_u32_e32 v237, vcc, 0, v247, vcc
	global_store_dwordx2 v[236:237], v[230:231], off
	global_store_dwordx2 v[236:237], v[232:233], off offset:32
	v_add_co_u32_e32 v236, vcc, 0x40100, v244
	v_addc_co_u32_e32 v237, vcc, 0, v245, vcc
	global_load_dwordx2 v[202:203], v[236:237], off
	global_load_dwordx2 v[204:205], v[236:237], off offset:32
	s_waitcnt vmcnt(4)
	v_lshlrev_b32_e32 v230, 16, v194
	v_and_b32_e32 v231, 0xffff0000, v194
	v_lshlrev_b32_e32 v232, 16, v195
	v_and_b32_e32 v233, 0xffff0000, v195
	v_pk_mul_f32 v[230:231], v[60:61], v[230:231]
	v_pk_mul_f32 v[232:233], v[62:63], v[232:233]
	v_cvt_pk_bf16_f32 v230, v230, v231
	v_cvt_pk_bf16_f32 v231, v232, v233
	v_lshlrev_b32_e32 v234, 16, v196
	v_and_b32_e32 v235, 0xffff0000, v196
	v_lshlrev_b32_e32 v236, 16, v197
	v_and_b32_e32 v237, 0xffff0000, v197
	v_pk_mul_f32 v[234:235], v[56:57], v[234:235]
	v_pk_mul_f32 v[236:237], v[58:59], v[236:237]
	v_cvt_pk_bf16_f32 v232, v234, v235
	v_cvt_pk_bf16_f32 v233, v236, v237
	v_add_co_u32_e32 v236, vcc, 0x40000, v246
	v_addc_co_u32_e32 v237, vcc, 0, v247, vcc
	global_store_dwordx2 v[236:237], v[230:231], off
	global_store_dwordx2 v[236:237], v[232:233], off offset:32
	v_add_co_u32_e32 v236, vcc, 0x48000, v244
	v_addc_co_u32_e32 v237, vcc, 0, v245, vcc
	global_load_dwordx2 v[194:195], v[236:237], off
	global_load_dwordx2 v[196:197], v[236:237], off offset:32
	s_waitcnt vmcnt(4)
	v_lshlrev_b32_e32 v230, 16, v202
	v_and_b32_e32 v231, 0xffff0000, v202
	v_lshlrev_b32_e32 v232, 16, v203
	v_and_b32_e32 v233, 0xffff0000, v203
	v_pk_mul_f32 v[230:231], v[52:53], v[230:231]
	v_pk_mul_f32 v[232:233], v[54:55], v[232:233]
	v_cvt_pk_bf16_f32 v230, v230, v231
	v_cvt_pk_bf16_f32 v231, v232, v233
	v_lshlrev_b32_e32 v234, 16, v204
	v_and_b32_e32 v235, 0xffff0000, v204
	v_lshlrev_b32_e32 v236, 16, v205
	v_and_b32_e32 v237, 0xffff0000, v205
	v_pk_mul_f32 v[234:235], v[48:49], v[234:235]
	v_pk_mul_f32 v[236:237], v[50:51], v[236:237]
	v_cvt_pk_bf16_f32 v232, v234, v235
	v_cvt_pk_bf16_f32 v233, v236, v237
	v_add_co_u32_e32 v236, vcc, 0x40100, v246
	v_addc_co_u32_e32 v237, vcc, 0, v247, vcc
	global_store_dwordx2 v[236:237], v[230:231], off
	global_store_dwordx2 v[236:237], v[232:233], off offset:32
	v_add_co_u32_e32 v236, vcc, 0x48100, v244
	v_addc_co_u32_e32 v237, vcc, 0, v245, vcc
	global_load_dwordx2 v[202:203], v[236:237], off
	global_load_dwordx2 v[204:205], v[236:237], off offset:32
	s_waitcnt vmcnt(4)
	v_lshlrev_b32_e32 v230, 16, v194
	v_and_b32_e32 v231, 0xffff0000, v194
	v_lshlrev_b32_e32 v232, 16, v195
	v_and_b32_e32 v233, 0xffff0000, v195
	v_pk_mul_f32 v[230:231], v[44:45], v[230:231]
	v_pk_mul_f32 v[232:233], v[46:47], v[232:233]
	v_cvt_pk_bf16_f32 v230, v230, v231
	v_cvt_pk_bf16_f32 v231, v232, v233
	v_lshlrev_b32_e32 v234, 16, v196
	v_and_b32_e32 v235, 0xffff0000, v196
	v_lshlrev_b32_e32 v236, 16, v197
	v_and_b32_e32 v237, 0xffff0000, v197
	v_pk_mul_f32 v[234:235], v[40:41], v[234:235]
	v_pk_mul_f32 v[236:237], v[42:43], v[236:237]
	v_cvt_pk_bf16_f32 v232, v234, v235
	v_cvt_pk_bf16_f32 v233, v236, v237
	v_add_co_u32_e32 v236, vcc, 0x48000, v246
	v_addc_co_u32_e32 v237, vcc, 0, v247, vcc
	global_store_dwordx2 v[236:237], v[230:231], off
	global_store_dwordx2 v[236:237], v[232:233], off offset:32
	v_add_co_u32_e32 v236, vcc, 0x50000, v244
	v_addc_co_u32_e32 v237, vcc, 0, v245, vcc
	global_load_dwordx2 v[194:195], v[236:237], off
	global_load_dwordx2 v[196:197], v[236:237], off offset:32
	s_waitcnt vmcnt(4)
	v_lshlrev_b32_e32 v230, 16, v202
	v_and_b32_e32 v231, 0xffff0000, v202
	v_lshlrev_b32_e32 v232, 16, v203
	v_and_b32_e32 v233, 0xffff0000, v203
	v_pk_mul_f32 v[230:231], v[36:37], v[230:231]
	v_pk_mul_f32 v[232:233], v[38:39], v[232:233]
	v_cvt_pk_bf16_f32 v230, v230, v231
	v_cvt_pk_bf16_f32 v231, v232, v233
	v_lshlrev_b32_e32 v234, 16, v204
	v_and_b32_e32 v235, 0xffff0000, v204
	v_lshlrev_b32_e32 v236, 16, v205
	v_and_b32_e32 v237, 0xffff0000, v205
	v_pk_mul_f32 v[234:235], v[32:33], v[234:235]
	v_pk_mul_f32 v[236:237], v[34:35], v[236:237]
	v_cvt_pk_bf16_f32 v232, v234, v235
	v_cvt_pk_bf16_f32 v233, v236, v237
	v_add_co_u32_e32 v236, vcc, 0x48100, v246
	v_addc_co_u32_e32 v237, vcc, 0, v247, vcc
	global_store_dwordx2 v[236:237], v[230:231], off
	global_store_dwordx2 v[236:237], v[232:233], off offset:32
	v_add_co_u32_e32 v236, vcc, 0x50100, v244
	v_addc_co_u32_e32 v237, vcc, 0, v245, vcc
	global_load_dwordx2 v[202:203], v[236:237], off
	global_load_dwordx2 v[204:205], v[236:237], off offset:32
	s_waitcnt vmcnt(4)
	v_lshlrev_b32_e32 v230, 16, v194
	v_and_b32_e32 v231, 0xffff0000, v194
	v_lshlrev_b32_e32 v232, 16, v195
	v_and_b32_e32 v233, 0xffff0000, v195
	v_pk_mul_f32 v[230:231], v[28:29], v[230:231]
	v_pk_mul_f32 v[232:233], v[30:31], v[232:233]
	v_cvt_pk_bf16_f32 v230, v230, v231
	v_cvt_pk_bf16_f32 v231, v232, v233
	v_lshlrev_b32_e32 v234, 16, v196
	v_and_b32_e32 v235, 0xffff0000, v196
	v_lshlrev_b32_e32 v236, 16, v197
	v_and_b32_e32 v237, 0xffff0000, v197
	v_pk_mul_f32 v[234:235], v[24:25], v[234:235]
	v_pk_mul_f32 v[236:237], v[26:27], v[236:237]
	v_cvt_pk_bf16_f32 v232, v234, v235
	v_cvt_pk_bf16_f32 v233, v236, v237
	v_add_co_u32_e32 v236, vcc, 0x50000, v246
	v_addc_co_u32_e32 v237, vcc, 0, v247, vcc
	global_store_dwordx2 v[236:237], v[230:231], off
	global_store_dwordx2 v[236:237], v[232:233], off offset:32
	v_add_co_u32_e32 v236, vcc, 0x58000, v244
	v_addc_co_u32_e32 v237, vcc, 0, v245, vcc
	global_load_dwordx2 v[194:195], v[236:237], off
	global_load_dwordx2 v[196:197], v[236:237], off offset:32
	s_waitcnt vmcnt(4)
	v_lshlrev_b32_e32 v230, 16, v202
	v_and_b32_e32 v231, 0xffff0000, v202
	v_lshlrev_b32_e32 v232, 16, v203
	v_and_b32_e32 v233, 0xffff0000, v203
	v_pk_mul_f32 v[230:231], v[20:21], v[230:231]
	v_pk_mul_f32 v[232:233], v[22:23], v[232:233]
	v_cvt_pk_bf16_f32 v230, v230, v231
	v_cvt_pk_bf16_f32 v231, v232, v233
	v_lshlrev_b32_e32 v234, 16, v204
	v_and_b32_e32 v235, 0xffff0000, v204
	v_lshlrev_b32_e32 v236, 16, v205
	v_and_b32_e32 v237, 0xffff0000, v205
	v_pk_mul_f32 v[234:235], v[16:17], v[234:235]
	v_pk_mul_f32 v[236:237], v[18:19], v[236:237]
	v_cvt_pk_bf16_f32 v232, v234, v235
	v_cvt_pk_bf16_f32 v233, v236, v237
	v_add_co_u32_e32 v236, vcc, 0x50100, v246
	v_addc_co_u32_e32 v237, vcc, 0, v247, vcc
	global_store_dwordx2 v[236:237], v[230:231], off
	global_store_dwordx2 v[236:237], v[232:233], off offset:32
	v_add_co_u32_e32 v236, vcc, 0x58100, v244
	v_addc_co_u32_e32 v237, vcc, 0, v245, vcc
	global_load_dwordx2 v[202:203], v[236:237], off
	global_load_dwordx2 v[204:205], v[236:237], off offset:32
	s_waitcnt vmcnt(4)
	v_lshlrev_b32_e32 v230, 16, v194
	v_and_b32_e32 v231, 0xffff0000, v194
	v_lshlrev_b32_e32 v232, 16, v195
	v_and_b32_e32 v233, 0xffff0000, v195
	v_pk_mul_f32 v[230:231], v[12:13], v[230:231]
	v_pk_mul_f32 v[232:233], v[14:15], v[232:233]
	v_cvt_pk_bf16_f32 v230, v230, v231
	v_cvt_pk_bf16_f32 v231, v232, v233
	v_lshlrev_b32_e32 v234, 16, v196
	v_and_b32_e32 v235, 0xffff0000, v196
	v_lshlrev_b32_e32 v236, 16, v197
	v_and_b32_e32 v237, 0xffff0000, v197
	v_pk_mul_f32 v[234:235], v[8:9], v[234:235]
	v_pk_mul_f32 v[236:237], v[10:11], v[236:237]
	v_cvt_pk_bf16_f32 v232, v234, v235
	v_cvt_pk_bf16_f32 v233, v236, v237
	v_add_co_u32_e32 v236, vcc, 0x58000, v246
	v_addc_co_u32_e32 v237, vcc, 0, v247, vcc
	global_store_dwordx2 v[236:237], v[230:231], off
	global_store_dwordx2 v[236:237], v[232:233], off offset:32
	s_waitcnt vmcnt(2)
	v_lshlrev_b32_e32 v230, 16, v202
	v_and_b32_e32 v231, 0xffff0000, v202
	v_lshlrev_b32_e32 v232, 16, v203
	v_and_b32_e32 v233, 0xffff0000, v203
	v_pk_mul_f32 v[230:231], v[4:5], v[230:231]
	v_pk_mul_f32 v[232:233], v[6:7], v[232:233]
	v_cvt_pk_bf16_f32 v230, v230, v231
	v_cvt_pk_bf16_f32 v231, v232, v233
	v_lshlrev_b32_e32 v234, 16, v204
	v_and_b32_e32 v235, 0xffff0000, v204
	v_lshlrev_b32_e32 v236, 16, v205
	v_and_b32_e32 v237, 0xffff0000, v205
	v_pk_mul_f32 v[234:235], v[0:1], v[234:235]
	v_pk_mul_f32 v[236:237], v[2:3], v[236:237]
	v_cvt_pk_bf16_f32 v232, v234, v235
	v_cvt_pk_bf16_f32 v233, v236, v237
	v_add_co_u32_e32 v236, vcc, 0x58100, v246
	v_addc_co_u32_e32 v237, vcc, 0, v247, vcc
	global_store_dwordx2 v[236:237], v[230:231], off
	global_store_dwordx2 v[236:237], v[232:233], off offset:32
	s_branch .LBB0_1065
.Lfb_no:
	s_cmp_lt_i32 s79, 22
	s_mov_b64 s[2:3], 0
	s_cbranch_scc1 .LBB0_117
	s_cmp_gt_i32 s79, 23
	s_cbranch_scc0 .LBB0_111
	s_cmp_gt_i32 s79, 24
	s_cbranch_scc0 .LBB0_108
	s_cmp_gt_i32 s79, 25
	s_cbranch_scc0 .LBB0_97
	s_cmp_eq_u32 s79, 26
	s_mov_b64 s[2:3], -1
	s_cbranch_scc0 .LBB0_96
	v_max_f32_e32 v137, v124, v124
	v_max_f32_e32 v137, 0, v137
	v_max_f32_e32 v140, v120, v120
	v_max_f32_e32 v140, 0, v140
	v_mul_f32_e32 v144, v137, v137
	v_max_f32_e32 v137, v125, v125
	v_mul_f32_e32 v152, v140, v140
	v_max_f32_e32 v137, 0, v137
	v_max_f32_e32 v140, v121, v121
	v_max_f32_e32 v140, 0, v140
	v_mul_f32_e32 v145, v137, v137
	v_max_f32_e32 v137, v126, v126
	v_mul_f32_e32 v166, v140, v140
	v_max_f32_e32 v137, 0, v137
	v_max_f32_e32 v140, v122, v122
	v_max_f32_e32 v140, 0, v140
	v_mul_f32_e32 v167, v137, v137
	v_max_f32_e32 v137, v127, v127
	v_mul_f32_e32 v168, v140, v140
	v_max_f32_e32 v137, 0, v137
	v_max_f32_e32 v140, v123, v123
	v_max_f32_e32 v140, 0, v140
	v_mul_f32_e32 v169, v137, v137
	v_ashrrev_i32_e32 v137, 31, v136
	v_mul_f32_e32 v170, v140, v140
	v_lshl_add_u64 v[140:141], v[136:137], 1, v[148:149]
	v_cvt_pk_bf16_f32 v144, v144, v145
	v_cvt_pk_bf16_f32 v145, v167, v169
	global_store_dwordx2 v[140:141], v[144:145], off
	v_cvt_pk_bf16_f32 v144, v152, v166
	v_cvt_pk_bf16_f32 v145, v168, v170
	global_store_dwordx2 v[140:141], v[144:145], off offset:32
	s_mov_b64 s[2:3], 0
